# same as the 16-group pre-pass version but FF1 sample tiles keep plain hid stores with the L2 write-back before the panel counter, and the FF2 owner keeps its acquire invalidate
# baseline (speedup 1.0000x reference)
.LBB0_1318:
	v_readlane_b32 s52, v243, 56
	s_add_u32 s54, s36, 0x62d8000
	s_addc_u32 s55, s37, 0
	s_add_u32 s56, s36, 0x7670000
	s_addc_u32 s57, s37, 0
	s_mov_b32 s58, 0x2000
	s_mov_b32 s59, 0
	s_lshl_b32 s53, s52, 13
	s_lshl_b32 s52, s52, 9
	s_addk_i32 s52, 0x2000
	v_add_u32_e32 v182, s16, v151
	v_lshlrev_b32_e32 v172, 6, v182
	v_lshl_add_u32 v172, v150, 4, v172
	v_mov_b32_e32 v173, 0
	v_lshl_add_u64 v[172:173], s[54:55], 0, v[172:173]
	global_load_dwordx4 v[198:201], v[172:173], off
	global_load_dwordx4 v[202:205], v[172:173], off offset:1024
	global_load_dwordx4 v[206:209], v[172:173], off offset:2048
	global_load_dwordx4 v[210:213], v[172:173], off offset:3072
	v_lshl_add_u64 v[172:173], v[172:173], 0, s[58:59]
	global_load_dwordx4 v[224:227], v[172:173], off
	global_load_dwordx4 v[228:231], v[172:173], off offset:1024
	global_load_dwordx4 v[232:235], v[172:173], off offset:2048
	global_load_dwordx4 v[236:239], v[172:173], off offset:3072
	v_lshlrev_b32_e32 v183, 2, v144
	v_lshlrev_b32_e32 v171, 1, v144
	v_lshl_add_u32 v197, v182, 13, v171
	v_xor_b32_e32 v194, 16, v221
	v_lshlrev_b32_e32 v194, 2, v194
	v_xor_b32_e32 v196, 32, v221
	v_lshlrev_b32_e32 v196, 2, v196
	v_cmp_gt_i32_e32 vcc, s33, v182
	v_add_u32_e32 v167, s52, v182
	v_add_u32_e32 v168, s53, v182
	v_cndmask_b32_e32 v167, v167, v168, vcc
	v_cmp_gt_i32_e32 vcc, s90, v167
	v_add_u32_e32 v168, 0xffffc000, v167
	v_lshrrev_b32_e32 v168, 3, v168
	v_ashrrev_i32_e32 v169, 11, v167
	v_add_u32_e32 v168, 8, v168
	v_cndmask_b32_e32 v167, v168, v169, vcc
	v_lshl_add_u32 v171, v167, 14, v183
	global_load_dwordx4 v[104:107], v171, s[6:7]
	global_load_dwordx4 v[108:111], v171, s[6:7] offset:16
	global_load_dwordx4 v[124:127], v171, s[6:7] offset:512
	global_load_dwordx4 v[120:123], v171, s[6:7] offset:528
	s_waitcnt vmcnt(4)
	v_add_f32_e32 v174, v198, v199
	v_add_f32_e32 v186, v200, v201
	v_add_f32_e32 v175, v202, v203
	v_add_f32_e32 v187, v204, v205
	v_add_f32_e32 v176, v206, v207
	v_add_f32_e32 v188, v208, v209
	v_add_f32_e32 v177, v210, v211
	v_add_f32_e32 v189, v212, v213
	v_add_f32_e32 v178, v224, v225
	v_add_f32_e32 v190, v226, v227
	v_add_f32_e32 v179, v228, v229
	v_add_f32_e32 v191, v230, v231
	v_add_f32_e32 v180, v232, v233
	v_add_f32_e32 v192, v234, v235
	v_add_f32_e32 v181, v236, v237
	v_add_f32_e32 v193, v238, v239
	v_add_f32_e32 v174, v174, v186
	v_add_f32_e32 v175, v175, v187
	v_add_f32_e32 v176, v176, v188
	v_add_f32_e32 v177, v177, v189
	v_add_f32_e32 v178, v178, v190
	v_add_f32_e32 v179, v179, v191
	v_add_f32_e32 v180, v180, v192
	v_add_f32_e32 v181, v181, v193
	ds_bpermute_b32 v186, v194, v174
	ds_bpermute_b32 v187, v194, v175
	ds_bpermute_b32 v188, v194, v176
	ds_bpermute_b32 v189, v194, v177
	ds_bpermute_b32 v190, v194, v178
	ds_bpermute_b32 v191, v194, v179
	ds_bpermute_b32 v192, v194, v180
	ds_bpermute_b32 v193, v194, v181
	v_or_b32_e32 v170, 16, v182
	v_cmp_gt_i32_e32 vcc, s33, v170
	v_add_u32_e32 v167, s52, v170
	v_add_u32_e32 v168, s53, v170
	v_cndmask_b32_e32 v167, v167, v168, vcc
	v_cmp_gt_i32_e32 vcc, s90, v167
	v_add_u32_e32 v168, 0xffffc000, v167
	v_lshrrev_b32_e32 v168, 3, v168
	v_ashrrev_i32_e32 v169, 11, v167
	v_add_u32_e32 v168, 8, v168
	v_cndmask_b32_e32 v167, v168, v169, vcc
	v_lshl_add_u32 v171, v167, 14, v183
	global_load_dwordx4 v[198:201], v171, s[6:7]
	global_load_dwordx4 v[202:205], v171, s[6:7] offset:16
	global_load_dwordx4 v[206:209], v171, s[6:7] offset:512
	global_load_dwordx4 v[210:213], v171, s[6:7] offset:528
	s_waitcnt lgkmcnt(0)
	v_add_f32_e32 v174, v174, v186
	v_add_f32_e32 v175, v175, v187
	v_add_f32_e32 v176, v176, v188
	v_add_f32_e32 v177, v177, v189
	v_add_f32_e32 v178, v178, v190
	v_add_f32_e32 v179, v179, v191
	v_add_f32_e32 v180, v180, v192
	v_add_f32_e32 v181, v181, v193
	ds_bpermute_b32 v186, v196, v174
	ds_bpermute_b32 v187, v196, v175
	ds_bpermute_b32 v188, v196, v176
	ds_bpermute_b32 v189, v196, v177
	ds_bpermute_b32 v190, v196, v178
	ds_bpermute_b32 v191, v196, v179
	ds_bpermute_b32 v192, v196, v180
	ds_bpermute_b32 v193, v196, v181
	v_or_b32_e32 v170, 32, v182
	v_cmp_gt_i32_e32 vcc, s33, v170
	v_add_u32_e32 v167, s52, v170
	v_add_u32_e32 v168, s53, v170
	v_cndmask_b32_e32 v167, v167, v168, vcc
	v_cmp_gt_i32_e32 vcc, s90, v167
	v_add_u32_e32 v168, 0xffffc000, v167
	v_lshrrev_b32_e32 v168, 3, v168
	v_ashrrev_i32_e32 v169, 11, v167
	v_add_u32_e32 v168, 8, v168
	v_cndmask_b32_e32 v167, v168, v169, vcc
	v_lshl_add_u32 v171, v167, 14, v183
	global_load_dwordx4 v[224:227], v171, s[6:7]
	global_load_dwordx4 v[228:231], v171, s[6:7] offset:16
	global_load_dwordx4 v[232:235], v171, s[6:7] offset:512
	global_load_dwordx4 v[236:239], v171, s[6:7] offset:528
	s_waitcnt lgkmcnt(0)
	v_add_f32_e32 v174, v174, v186
	v_add_f32_e32 v175, v175, v187
	v_add_f32_e32 v176, v176, v188
	v_add_f32_e32 v177, v177, v189
	v_add_f32_e32 v178, v178, v190
	v_add_f32_e32 v179, v179, v191
	v_add_f32_e32 v180, v180, v192
	v_add_f32_e32 v181, v181, v193
	v_fmamk_f32 v174, v174, 0x3a800000, v216
	v_fmamk_f32 v175, v175, 0x3a800000, v216
	v_fmamk_f32 v176, v176, 0x3a800000, v216
	v_fmamk_f32 v177, v177, 0x3a800000, v216
	v_fmamk_f32 v178, v178, 0x3a800000, v216
	v_fmamk_f32 v179, v179, 0x3a800000, v216
	v_fmamk_f32 v180, v180, 0x3a800000, v216
	v_fmamk_f32 v181, v181, 0x3a800000, v216
	v_rsq_f32_e32 v174, v174
	v_rsq_f32_e32 v175, v175
	v_rsq_f32_e32 v176, v176
	v_rsq_f32_e32 v177, v177
	v_rsq_f32_e32 v178, v178
	v_rsq_f32_e32 v179, v179
	v_rsq_f32_e32 v180, v180
	v_rsq_f32_e32 v181, v181
	s_nop 0
	s_waitcnt vmcnt(8)
	v_pk_fma_f32 v[142:143], v[142:143], v[174:175], v[106:107] op_sel_hi:[1,0,1]
	v_pk_fma_f32 v[140:141], v[140:141], v[174:175], v[104:105] op_sel_hi:[1,0,1]
	v_pk_fma_f32 v[138:139], v[138:139], v[174:175], v[110:111] op_sel_hi:[1,0,1]
	v_pk_fma_f32 v[136:137], v[136:137], v[174:175], v[108:109] op_sel_hi:[1,0,1]
	v_pk_fma_f32 v[134:135], v[134:135], v[174:175], v[126:127] op_sel_hi:[1,0,1]
	v_pk_fma_f32 v[132:133], v[132:133], v[174:175], v[124:125] op_sel_hi:[1,0,1]
	v_pk_fma_f32 v[130:131], v[130:131], v[174:175], v[122:123] op_sel_hi:[1,0,1]
	v_pk_fma_f32 v[128:129], v[128:129], v[174:175], v[120:121] op_sel_hi:[1,0,1]
	v_max_f32_e32 v140, 0, v140
	v_max_f32_e32 v141, 0, v141
	v_max_f32_e32 v142, 0, v142
	v_max_f32_e32 v143, 0, v143
	v_max_f32_e32 v136, 0, v136
	v_max_f32_e32 v137, 0, v137
	v_max_f32_e32 v138, 0, v138
	v_max_f32_e32 v139, 0, v139
	v_mul_f32_e32 v140, v140, v140
	v_mul_f32_e32 v141, v141, v141
	v_mul_f32_e32 v142, v142, v142
	v_mul_f32_e32 v143, v143, v143
	v_mul_f32_e32 v136, v136, v136
	v_mul_f32_e32 v137, v137, v137
	v_mul_f32_e32 v138, v138, v138
	v_mul_f32_e32 v139, v139, v139
	v_cvt_pk_bf16_f32 v140, v140, v141
	v_cvt_pk_bf16_f32 v141, v142, v143
	v_cvt_pk_bf16_f32 v142, v136, v137
	v_cvt_pk_bf16_f32 v143, v138, v139
	global_store_dwordx4 v197, v[140:143], s[56:57]
	v_max_f32_e32 v132, 0, v132
	v_max_f32_e32 v133, 0, v133
	v_max_f32_e32 v134, 0, v134
	v_max_f32_e32 v135, 0, v135
	v_max_f32_e32 v128, 0, v128
	v_max_f32_e32 v129, 0, v129
	v_max_f32_e32 v130, 0, v130
	v_max_f32_e32 v131, 0, v131
	v_mul_f32_e32 v132, v132, v132
	v_mul_f32_e32 v133, v133, v133
	v_mul_f32_e32 v134, v134, v134
	v_mul_f32_e32 v135, v135, v135
	v_mul_f32_e32 v128, v128, v128
	v_mul_f32_e32 v129, v129, v129
	v_mul_f32_e32 v130, v130, v130
	v_mul_f32_e32 v131, v131, v131
	v_cvt_pk_bf16_f32 v132, v132, v133
	v_cvt_pk_bf16_f32 v133, v134, v135
	v_cvt_pk_bf16_f32 v134, v128, v129
	v_cvt_pk_bf16_f32 v135, v130, v131
	global_store_dwordx4 v197, v[132:135], s[56:57] offset:256
	v_add_u32_e32 v240, 0x20000, v197
	v_or_b32_e32 v170, 48, v182
	v_cmp_gt_i32_e32 vcc, s33, v170
	v_add_u32_e32 v167, s52, v170
	v_add_u32_e32 v168, s53, v170
	v_cndmask_b32_e32 v167, v167, v168, vcc
	v_cmp_gt_i32_e32 vcc, s90, v167
	v_add_u32_e32 v168, 0xffffc000, v167
	v_lshrrev_b32_e32 v168, 3, v168
	v_ashrrev_i32_e32 v169, 11, v167
	v_add_u32_e32 v168, 8, v168
	v_cndmask_b32_e32 v167, v168, v169, vcc
	v_lshl_add_u32 v171, v167, 14, v183
	global_load_dwordx4 v[104:107], v171, s[6:7]
	global_load_dwordx4 v[108:111], v171, s[6:7] offset:16
	global_load_dwordx4 v[124:127], v171, s[6:7] offset:512
	global_load_dwordx4 v[120:123], v171, s[6:7] offset:528
	s_waitcnt vmcnt(10)
	v_pk_fma_f32 v[118:119], v[118:119], v[174:175], v[200:201] op_sel:[0,1,0] op_sel_hi:[1,1,1]
	v_pk_fma_f32 v[116:117], v[116:117], v[174:175], v[198:199] op_sel:[0,1,0] op_sel_hi:[1,1,1]
	v_pk_fma_f32 v[114:115], v[114:115], v[174:175], v[204:205] op_sel:[0,1,0] op_sel_hi:[1,1,1]
	v_pk_fma_f32 v[112:113], v[112:113], v[174:175], v[202:203] op_sel:[0,1,0] op_sel_hi:[1,1,1]
	v_pk_fma_f32 v[102:103], v[102:103], v[174:175], v[208:209] op_sel:[0,1,0] op_sel_hi:[1,1,1]
	v_pk_fma_f32 v[100:101], v[100:101], v[174:175], v[206:207] op_sel:[0,1,0] op_sel_hi:[1,1,1]
	v_pk_fma_f32 v[98:99], v[98:99], v[174:175], v[212:213] op_sel:[0,1,0] op_sel_hi:[1,1,1]
	v_pk_fma_f32 v[96:97], v[96:97], v[174:175], v[210:211] op_sel:[0,1,0] op_sel_hi:[1,1,1]
	v_max_f32_e32 v116, 0, v116
	v_max_f32_e32 v117, 0, v117
	v_max_f32_e32 v118, 0, v118
	v_max_f32_e32 v119, 0, v119
	v_max_f32_e32 v112, 0, v112
	v_max_f32_e32 v113, 0, v113
	v_max_f32_e32 v114, 0, v114
	v_max_f32_e32 v115, 0, v115
	v_mul_f32_e32 v116, v116, v116
	v_mul_f32_e32 v117, v117, v117
	v_mul_f32_e32 v118, v118, v118
	v_mul_f32_e32 v119, v119, v119
	v_mul_f32_e32 v112, v112, v112
	v_mul_f32_e32 v113, v113, v113
	v_mul_f32_e32 v114, v114, v114
	v_mul_f32_e32 v115, v115, v115
	v_cvt_pk_bf16_f32 v116, v116, v117
	v_cvt_pk_bf16_f32 v117, v118, v119
	v_cvt_pk_bf16_f32 v118, v112, v113
	v_cvt_pk_bf16_f32 v119, v114, v115
	global_store_dwordx4 v240, v[116:119], s[56:57]
	v_max_f32_e32 v100, 0, v100
	v_max_f32_e32 v101, 0, v101
	v_max_f32_e32 v102, 0, v102
	v_max_f32_e32 v103, 0, v103
	v_max_f32_e32 v96, 0, v96
	v_max_f32_e32 v97, 0, v97
	v_max_f32_e32 v98, 0, v98
	v_max_f32_e32 v99, 0, v99
	v_mul_f32_e32 v100, v100, v100
	v_mul_f32_e32 v101, v101, v101
	v_mul_f32_e32 v102, v102, v102
	v_mul_f32_e32 v103, v103, v103
	v_mul_f32_e32 v96, v96, v96
	v_mul_f32_e32 v97, v97, v97
	v_mul_f32_e32 v98, v98, v98
	v_mul_f32_e32 v99, v99, v99
	v_cvt_pk_bf16_f32 v100, v100, v101
	v_cvt_pk_bf16_f32 v101, v102, v103
	v_cvt_pk_bf16_f32 v102, v96, v97
	v_cvt_pk_bf16_f32 v103, v98, v99
	global_store_dwordx4 v240, v[100:103], s[56:57] offset:256
	v_add_u32_e32 v197, 0x20000, v240
	v_add_u32_e32 v170, 0x80, v182
	v_cmp_gt_i32_e32 vcc, s33, v170
	v_add_u32_e32 v167, s52, v170
	v_add_u32_e32 v168, s53, v170
	v_cndmask_b32_e32 v167, v167, v168, vcc
	v_cmp_gt_i32_e32 vcc, s90, v167
	v_add_u32_e32 v168, 0xffffc000, v167
	v_lshrrev_b32_e32 v168, 3, v168
	v_ashrrev_i32_e32 v169, 11, v167
	v_add_u32_e32 v168, 8, v168
	v_cndmask_b32_e32 v167, v168, v169, vcc
	v_lshl_add_u32 v171, v167, 14, v183
	global_load_dwordx4 v[198:201], v171, s[6:7]
	global_load_dwordx4 v[202:205], v171, s[6:7] offset:16
	global_load_dwordx4 v[206:209], v171, s[6:7] offset:512
	global_load_dwordx4 v[210:213], v171, s[6:7] offset:528
	s_waitcnt vmcnt(12)
	v_pk_fma_f32 v[94:95], v[94:95], v[176:177], v[226:227] op_sel_hi:[1,0,1]
	v_pk_fma_f32 v[92:93], v[92:93], v[176:177], v[224:225] op_sel_hi:[1,0,1]
	v_pk_fma_f32 v[90:91], v[90:91], v[176:177], v[230:231] op_sel_hi:[1,0,1]
	v_pk_fma_f32 v[88:89], v[88:89], v[176:177], v[228:229] op_sel_hi:[1,0,1]
	v_pk_fma_f32 v[86:87], v[86:87], v[176:177], v[234:235] op_sel_hi:[1,0,1]
	v_pk_fma_f32 v[84:85], v[84:85], v[176:177], v[232:233] op_sel_hi:[1,0,1]
	v_pk_fma_f32 v[82:83], v[82:83], v[176:177], v[238:239] op_sel_hi:[1,0,1]
	v_pk_fma_f32 v[80:81], v[80:81], v[176:177], v[236:237] op_sel_hi:[1,0,1]
	v_max_f32_e32 v92, 0, v92
	v_max_f32_e32 v93, 0, v93
	v_max_f32_e32 v94, 0, v94
	v_max_f32_e32 v95, 0, v95
	v_max_f32_e32 v88, 0, v88
	v_max_f32_e32 v89, 0, v89
	v_max_f32_e32 v90, 0, v90
	v_max_f32_e32 v91, 0, v91
	v_mul_f32_e32 v92, v92, v92
	v_mul_f32_e32 v93, v93, v93
	v_mul_f32_e32 v94, v94, v94
	v_mul_f32_e32 v95, v95, v95
	v_mul_f32_e32 v88, v88, v88
	v_mul_f32_e32 v89, v89, v89
	v_mul_f32_e32 v90, v90, v90
	v_mul_f32_e32 v91, v91, v91
	v_cvt_pk_bf16_f32 v92, v92, v93
	v_cvt_pk_bf16_f32 v93, v94, v95
	v_cvt_pk_bf16_f32 v94, v88, v89
	v_cvt_pk_bf16_f32 v95, v90, v91
	global_store_dwordx4 v197, v[92:95], s[56:57]
	v_max_f32_e32 v84, 0, v84
	v_max_f32_e32 v85, 0, v85
	v_max_f32_e32 v86, 0, v86
	v_max_f32_e32 v87, 0, v87
	v_max_f32_e32 v80, 0, v80
	v_max_f32_e32 v81, 0, v81
	v_max_f32_e32 v82, 0, v82
	v_max_f32_e32 v83, 0, v83
	v_mul_f32_e32 v84, v84, v84
	v_mul_f32_e32 v85, v85, v85
	v_mul_f32_e32 v86, v86, v86
	v_mul_f32_e32 v87, v87, v87
	v_mul_f32_e32 v80, v80, v80
	v_mul_f32_e32 v81, v81, v81
	v_mul_f32_e32 v82, v82, v82
	v_mul_f32_e32 v83, v83, v83
	v_cvt_pk_bf16_f32 v84, v84, v85
	v_cvt_pk_bf16_f32 v85, v86, v87
	v_cvt_pk_bf16_f32 v86, v80, v81
	v_cvt_pk_bf16_f32 v87, v82, v83
	global_store_dwordx4 v197, v[84:87], s[56:57] offset:256
	v_add_u32_e32 v240, 0x20000, v197
	v_add_u32_e32 v170, 0x90, v182
	v_cmp_gt_i32_e32 vcc, s33, v170
	v_add_u32_e32 v167, s52, v170
	v_add_u32_e32 v168, s53, v170
	v_cndmask_b32_e32 v167, v167, v168, vcc
	v_cmp_gt_i32_e32 vcc, s90, v167
	v_add_u32_e32 v168, 0xffffc000, v167
	v_lshrrev_b32_e32 v168, 3, v168
	v_ashrrev_i32_e32 v169, 11, v167
	v_add_u32_e32 v168, 8, v168
	v_cndmask_b32_e32 v167, v168, v169, vcc
	v_lshl_add_u32 v171, v167, 14, v183
	global_load_dwordx4 v[224:227], v171, s[6:7]
	global_load_dwordx4 v[228:231], v171, s[6:7] offset:16
	global_load_dwordx4 v[232:235], v171, s[6:7] offset:512
	global_load_dwordx4 v[236:239], v171, s[6:7] offset:528
	s_waitcnt vmcnt(12)
	v_pk_fma_f32 v[78:79], v[78:79], v[176:177], v[106:107] op_sel:[0,1,0] op_sel_hi:[1,1,1]
	v_pk_fma_f32 v[76:77], v[76:77], v[176:177], v[104:105] op_sel:[0,1,0] op_sel_hi:[1,1,1]
	v_pk_fma_f32 v[74:75], v[74:75], v[176:177], v[110:111] op_sel:[0,1,0] op_sel_hi:[1,1,1]
	v_pk_fma_f32 v[72:73], v[72:73], v[176:177], v[108:109] op_sel:[0,1,0] op_sel_hi:[1,1,1]
	v_pk_fma_f32 v[70:71], v[70:71], v[176:177], v[126:127] op_sel:[0,1,0] op_sel_hi:[1,1,1]
	v_pk_fma_f32 v[68:69], v[68:69], v[176:177], v[124:125] op_sel:[0,1,0] op_sel_hi:[1,1,1]
	v_pk_fma_f32 v[66:67], v[66:67], v[176:177], v[122:123] op_sel:[0,1,0] op_sel_hi:[1,1,1]
	v_pk_fma_f32 v[64:65], v[64:65], v[176:177], v[120:121] op_sel:[0,1,0] op_sel_hi:[1,1,1]
	v_max_f32_e32 v76, 0, v76
	v_max_f32_e32 v77, 0, v77
	v_max_f32_e32 v78, 0, v78
	v_max_f32_e32 v79, 0, v79
	v_max_f32_e32 v72, 0, v72
	v_max_f32_e32 v73, 0, v73
	v_max_f32_e32 v74, 0, v74
	v_max_f32_e32 v75, 0, v75
	v_mul_f32_e32 v76, v76, v76
	v_mul_f32_e32 v77, v77, v77
	v_mul_f32_e32 v78, v78, v78
	v_mul_f32_e32 v79, v79, v79
	v_mul_f32_e32 v72, v72, v72
	v_mul_f32_e32 v73, v73, v73
	v_mul_f32_e32 v74, v74, v74
	v_mul_f32_e32 v75, v75, v75
	v_cvt_pk_bf16_f32 v76, v76, v77
	v_cvt_pk_bf16_f32 v77, v78, v79
	v_cvt_pk_bf16_f32 v78, v72, v73
	v_cvt_pk_bf16_f32 v79, v74, v75
	global_store_dwordx4 v240, v[76:79], s[56:57]
	v_max_f32_e32 v68, 0, v68
	v_max_f32_e32 v69, 0, v69
	v_max_f32_e32 v70, 0, v70
	v_max_f32_e32 v71, 0, v71
	v_max_f32_e32 v64, 0, v64
	v_max_f32_e32 v65, 0, v65
	v_max_f32_e32 v66, 0, v66
	v_max_f32_e32 v67, 0, v67
	v_mul_f32_e32 v68, v68, v68
	v_mul_f32_e32 v69, v69, v69
	v_mul_f32_e32 v70, v70, v70
	v_mul_f32_e32 v71, v71, v71
	v_mul_f32_e32 v64, v64, v64
	v_mul_f32_e32 v65, v65, v65
	v_mul_f32_e32 v66, v66, v66
	v_mul_f32_e32 v67, v67, v67
	v_cvt_pk_bf16_f32 v68, v68, v69
	v_cvt_pk_bf16_f32 v69, v70, v71
	v_cvt_pk_bf16_f32 v70, v64, v65
	v_cvt_pk_bf16_f32 v71, v66, v67
	global_store_dwordx4 v240, v[68:71], s[56:57] offset:256
	v_add_u32_e32 v197, 0xa0000, v240
	v_add_u32_e32 v170, 0xa0, v182
	v_cmp_gt_i32_e32 vcc, s33, v170
	v_add_u32_e32 v167, s52, v170
	v_add_u32_e32 v168, s53, v170
	v_cndmask_b32_e32 v167, v167, v168, vcc
	v_cmp_gt_i32_e32 vcc, s90, v167
	v_add_u32_e32 v168, 0xffffc000, v167
	v_lshrrev_b32_e32 v168, 3, v168
	v_ashrrev_i32_e32 v169, 11, v167
	v_add_u32_e32 v168, 8, v168
	v_cndmask_b32_e32 v167, v168, v169, vcc
	v_lshl_add_u32 v171, v167, 14, v183
	global_load_dwordx4 v[104:107], v171, s[6:7]
	global_load_dwordx4 v[108:111], v171, s[6:7] offset:16
	global_load_dwordx4 v[124:127], v171, s[6:7] offset:512
	global_load_dwordx4 v[120:123], v171, s[6:7] offset:528
	s_waitcnt vmcnt(12)
	v_pk_fma_f32 v[62:63], v[62:63], v[178:179], v[200:201] op_sel_hi:[1,0,1]
	v_pk_fma_f32 v[60:61], v[60:61], v[178:179], v[198:199] op_sel_hi:[1,0,1]
	v_pk_fma_f32 v[58:59], v[58:59], v[178:179], v[204:205] op_sel_hi:[1,0,1]
	v_pk_fma_f32 v[56:57], v[56:57], v[178:179], v[202:203] op_sel_hi:[1,0,1]
	v_pk_fma_f32 v[54:55], v[54:55], v[178:179], v[208:209] op_sel_hi:[1,0,1]
	v_pk_fma_f32 v[52:53], v[52:53], v[178:179], v[206:207] op_sel_hi:[1,0,1]
	v_pk_fma_f32 v[50:51], v[50:51], v[178:179], v[212:213] op_sel_hi:[1,0,1]
	v_pk_fma_f32 v[48:49], v[48:49], v[178:179], v[210:211] op_sel_hi:[1,0,1]
	v_max_f32_e32 v60, 0, v60
	v_max_f32_e32 v61, 0, v61
	v_max_f32_e32 v62, 0, v62
	v_max_f32_e32 v63, 0, v63
	v_max_f32_e32 v56, 0, v56
	v_max_f32_e32 v57, 0, v57
	v_max_f32_e32 v58, 0, v58
	v_max_f32_e32 v59, 0, v59
	v_mul_f32_e32 v60, v60, v60
	v_mul_f32_e32 v61, v61, v61
	v_mul_f32_e32 v62, v62, v62
	v_mul_f32_e32 v63, v63, v63
	v_mul_f32_e32 v56, v56, v56
	v_mul_f32_e32 v57, v57, v57
	v_mul_f32_e32 v58, v58, v58
	v_mul_f32_e32 v59, v59, v59
	v_cvt_pk_bf16_f32 v60, v60, v61
	v_cvt_pk_bf16_f32 v61, v62, v63
	v_cvt_pk_bf16_f32 v62, v56, v57
	v_cvt_pk_bf16_f32 v63, v58, v59
	global_store_dwordx4 v197, v[60:63], s[56:57]
	v_max_f32_e32 v52, 0, v52
	v_max_f32_e32 v53, 0, v53
	v_max_f32_e32 v54, 0, v54
	v_max_f32_e32 v55, 0, v55
	v_max_f32_e32 v48, 0, v48
	v_max_f32_e32 v49, 0, v49
	v_max_f32_e32 v50, 0, v50
	v_max_f32_e32 v51, 0, v51
	v_mul_f32_e32 v52, v52, v52
	v_mul_f32_e32 v53, v53, v53
	v_mul_f32_e32 v54, v54, v54
	v_mul_f32_e32 v55, v55, v55
	v_mul_f32_e32 v48, v48, v48
	v_mul_f32_e32 v49, v49, v49
	v_mul_f32_e32 v50, v50, v50
	v_mul_f32_e32 v51, v51, v51
	v_cvt_pk_bf16_f32 v52, v52, v53
	v_cvt_pk_bf16_f32 v53, v54, v55
	v_cvt_pk_bf16_f32 v54, v48, v49
	v_cvt_pk_bf16_f32 v55, v50, v51
	global_store_dwordx4 v197, v[52:55], s[56:57] offset:256
	v_add_u32_e32 v240, 0x20000, v197
	v_add_u32_e32 v170, 0xb0, v182
	v_cmp_gt_i32_e32 vcc, s33, v170
	v_add_u32_e32 v167, s52, v170
	v_add_u32_e32 v168, s53, v170
	v_cndmask_b32_e32 v167, v167, v168, vcc
	v_cmp_gt_i32_e32 vcc, s90, v167
	v_add_u32_e32 v168, 0xffffc000, v167
	v_lshrrev_b32_e32 v168, 3, v168
	v_ashrrev_i32_e32 v169, 11, v167
	v_add_u32_e32 v168, 8, v168
	v_cndmask_b32_e32 v167, v168, v169, vcc
	v_lshl_add_u32 v171, v167, 14, v183
	global_load_dwordx4 v[198:201], v171, s[6:7]
	global_load_dwordx4 v[202:205], v171, s[6:7] offset:16
	global_load_dwordx4 v[206:209], v171, s[6:7] offset:512
	global_load_dwordx4 v[210:213], v171, s[6:7] offset:528
	s_waitcnt vmcnt(12)
	v_pk_fma_f32 v[46:47], v[46:47], v[178:179], v[226:227] op_sel:[0,1,0] op_sel_hi:[1,1,1]
	v_pk_fma_f32 v[44:45], v[44:45], v[178:179], v[224:225] op_sel:[0,1,0] op_sel_hi:[1,1,1]
	v_pk_fma_f32 v[42:43], v[42:43], v[178:179], v[230:231] op_sel:[0,1,0] op_sel_hi:[1,1,1]
	v_pk_fma_f32 v[40:41], v[40:41], v[178:179], v[228:229] op_sel:[0,1,0] op_sel_hi:[1,1,1]
	v_pk_fma_f32 v[38:39], v[38:39], v[178:179], v[234:235] op_sel:[0,1,0] op_sel_hi:[1,1,1]
	v_pk_fma_f32 v[36:37], v[36:37], v[178:179], v[232:233] op_sel:[0,1,0] op_sel_hi:[1,1,1]
	v_pk_fma_f32 v[34:35], v[34:35], v[178:179], v[238:239] op_sel:[0,1,0] op_sel_hi:[1,1,1]
	v_pk_fma_f32 v[32:33], v[32:33], v[178:179], v[236:237] op_sel:[0,1,0] op_sel_hi:[1,1,1]
	v_max_f32_e32 v44, 0, v44
	v_max_f32_e32 v45, 0, v45
	v_max_f32_e32 v46, 0, v46
	v_max_f32_e32 v47, 0, v47
	v_max_f32_e32 v40, 0, v40
	v_max_f32_e32 v41, 0, v41
	v_max_f32_e32 v42, 0, v42
	v_max_f32_e32 v43, 0, v43
	v_mul_f32_e32 v44, v44, v44
	v_mul_f32_e32 v45, v45, v45
	v_mul_f32_e32 v46, v46, v46
	v_mul_f32_e32 v47, v47, v47
	v_mul_f32_e32 v40, v40, v40
	v_mul_f32_e32 v41, v41, v41
	v_mul_f32_e32 v42, v42, v42
	v_mul_f32_e32 v43, v43, v43
	v_cvt_pk_bf16_f32 v44, v44, v45
	v_cvt_pk_bf16_f32 v45, v46, v47
	v_cvt_pk_bf16_f32 v46, v40, v41
	v_cvt_pk_bf16_f32 v47, v42, v43
	global_store_dwordx4 v240, v[44:47], s[56:57]
	v_max_f32_e32 v36, 0, v36
	v_max_f32_e32 v37, 0, v37
	v_max_f32_e32 v38, 0, v38
	v_max_f32_e32 v39, 0, v39
	v_max_f32_e32 v32, 0, v32
	v_max_f32_e32 v33, 0, v33
	v_max_f32_e32 v34, 0, v34
	v_max_f32_e32 v35, 0, v35
	v_mul_f32_e32 v36, v36, v36
	v_mul_f32_e32 v37, v37, v37
	v_mul_f32_e32 v38, v38, v38
	v_mul_f32_e32 v39, v39, v39
	v_mul_f32_e32 v32, v32, v32
	v_mul_f32_e32 v33, v33, v33
	v_mul_f32_e32 v34, v34, v34
	v_mul_f32_e32 v35, v35, v35
	v_cvt_pk_bf16_f32 v36, v36, v37
	v_cvt_pk_bf16_f32 v37, v38, v39
	v_cvt_pk_bf16_f32 v38, v32, v33
	v_cvt_pk_bf16_f32 v39, v34, v35
	global_store_dwordx4 v240, v[36:39], s[56:57] offset:256
	v_add_u32_e32 v197, 0x20000, v240
	s_waitcnt vmcnt(8)
	v_pk_fma_f32 v[30:31], v[30:31], v[180:181], v[106:107] op_sel_hi:[1,0,1]
	v_pk_fma_f32 v[28:29], v[28:29], v[180:181], v[104:105] op_sel_hi:[1,0,1]
	v_pk_fma_f32 v[26:27], v[26:27], v[180:181], v[110:111] op_sel_hi:[1,0,1]
	v_pk_fma_f32 v[24:25], v[24:25], v[180:181], v[108:109] op_sel_hi:[1,0,1]
	v_pk_fma_f32 v[22:23], v[22:23], v[180:181], v[126:127] op_sel_hi:[1,0,1]
	v_pk_fma_f32 v[20:21], v[20:21], v[180:181], v[124:125] op_sel_hi:[1,0,1]
	v_pk_fma_f32 v[18:19], v[18:19], v[180:181], v[122:123] op_sel_hi:[1,0,1]
	v_pk_fma_f32 v[16:17], v[16:17], v[180:181], v[120:121] op_sel_hi:[1,0,1]
	v_max_f32_e32 v28, 0, v28
	v_max_f32_e32 v29, 0, v29
	v_max_f32_e32 v30, 0, v30
	v_max_f32_e32 v31, 0, v31
	v_max_f32_e32 v24, 0, v24
	v_max_f32_e32 v25, 0, v25
	v_max_f32_e32 v26, 0, v26
	v_max_f32_e32 v27, 0, v27
	v_mul_f32_e32 v28, v28, v28
	v_mul_f32_e32 v29, v29, v29
	v_mul_f32_e32 v30, v30, v30
	v_mul_f32_e32 v31, v31, v31
	v_mul_f32_e32 v24, v24, v24
	v_mul_f32_e32 v25, v25, v25
	v_mul_f32_e32 v26, v26, v26
	v_mul_f32_e32 v27, v27, v27
	v_cvt_pk_bf16_f32 v28, v28, v29
	v_cvt_pk_bf16_f32 v29, v30, v31
	v_cvt_pk_bf16_f32 v30, v24, v25
	v_cvt_pk_bf16_f32 v31, v26, v27
	global_store_dwordx4 v197, v[28:31], s[56:57]
	v_max_f32_e32 v20, 0, v20
	v_max_f32_e32 v21, 0, v21
	v_max_f32_e32 v22, 0, v22
	v_max_f32_e32 v23, 0, v23
	v_max_f32_e32 v16, 0, v16
	v_max_f32_e32 v17, 0, v17
	v_max_f32_e32 v18, 0, v18
	v_max_f32_e32 v19, 0, v19
	v_mul_f32_e32 v20, v20, v20
	v_mul_f32_e32 v21, v21, v21
	v_mul_f32_e32 v22, v22, v22
	v_mul_f32_e32 v23, v23, v23
	v_mul_f32_e32 v16, v16, v16
	v_mul_f32_e32 v17, v17, v17
	v_mul_f32_e32 v18, v18, v18
	v_mul_f32_e32 v19, v19, v19
	v_cvt_pk_bf16_f32 v20, v20, v21
	v_cvt_pk_bf16_f32 v21, v22, v23
	v_cvt_pk_bf16_f32 v22, v16, v17
	v_cvt_pk_bf16_f32 v23, v18, v19
	global_store_dwordx4 v197, v[20:23], s[56:57] offset:256
	v_add_u32_e32 v240, 0x20000, v197
	s_waitcnt vmcnt(4)
	v_pk_fma_f32 v[14:15], v[14:15], v[180:181], v[200:201] op_sel:[0,1,0] op_sel_hi:[1,1,1]
	v_pk_fma_f32 v[12:13], v[12:13], v[180:181], v[198:199] op_sel:[0,1,0] op_sel_hi:[1,1,1]
	v_pk_fma_f32 v[10:11], v[10:11], v[180:181], v[204:205] op_sel:[0,1,0] op_sel_hi:[1,1,1]
	v_pk_fma_f32 v[8:9], v[8:9], v[180:181], v[202:203] op_sel:[0,1,0] op_sel_hi:[1,1,1]
	v_pk_fma_f32 v[6:7], v[6:7], v[180:181], v[208:209] op_sel:[0,1,0] op_sel_hi:[1,1,1]
	v_pk_fma_f32 v[4:5], v[4:5], v[180:181], v[206:207] op_sel:[0,1,0] op_sel_hi:[1,1,1]
	v_pk_fma_f32 v[2:3], v[2:3], v[180:181], v[212:213] op_sel:[0,1,0] op_sel_hi:[1,1,1]
	v_pk_fma_f32 v[0:1], v[0:1], v[180:181], v[210:211] op_sel:[0,1,0] op_sel_hi:[1,1,1]
	v_max_f32_e32 v12, 0, v12
	v_max_f32_e32 v13, 0, v13
	v_max_f32_e32 v14, 0, v14
	v_max_f32_e32 v15, 0, v15
	v_max_f32_e32 v8, 0, v8
	v_max_f32_e32 v9, 0, v9
	v_max_f32_e32 v10, 0, v10
	v_max_f32_e32 v11, 0, v11
	v_mul_f32_e32 v12, v12, v12
	v_mul_f32_e32 v13, v13, v13
	v_mul_f32_e32 v14, v14, v14
	v_mul_f32_e32 v15, v15, v15
	v_mul_f32_e32 v8, v8, v8
	v_mul_f32_e32 v9, v9, v9
	v_mul_f32_e32 v10, v10, v10
	v_mul_f32_e32 v11, v11, v11
	v_cvt_pk_bf16_f32 v12, v12, v13
	v_cvt_pk_bf16_f32 v13, v14, v15
	v_cvt_pk_bf16_f32 v14, v8, v9
	v_cvt_pk_bf16_f32 v15, v10, v11
	global_store_dwordx4 v240, v[12:15], s[56:57]
	v_max_f32_e32 v4, 0, v4
	v_max_f32_e32 v5, 0, v5
	v_max_f32_e32 v6, 0, v6
	v_max_f32_e32 v7, 0, v7
	v_max_f32_e32 v0, 0, v0
	v_max_f32_e32 v1, 0, v1
	v_max_f32_e32 v2, 0, v2
	v_max_f32_e32 v3, 0, v3
	v_mul_f32_e32 v4, v4, v4
	v_mul_f32_e32 v5, v5, v5
	v_mul_f32_e32 v6, v6, v6
	v_mul_f32_e32 v7, v7, v7
	v_mul_f32_e32 v0, v0, v0
	v_mul_f32_e32 v1, v1, v1
	v_mul_f32_e32 v2, v2, v2
	v_mul_f32_e32 v3, v3, v3
	v_cvt_pk_bf16_f32 v4, v4, v5
	v_cvt_pk_bf16_f32 v5, v6, v7
	v_cvt_pk_bf16_f32 v6, v0, v1
	v_cvt_pk_bf16_f32 v7, v2, v3
	global_store_dwordx4 v240, v[4:7], s[56:57] offset:256
	s_or_b32 s3, s1, s0
	s_lshl_b32 s0, s22, 6
	s_ashr_i32 s1, s0, 31
	s_lshl_b64 s[0:1], s[0:1], 2
	s_add_u32 s0, s36, s0
	s_addc_u32 s1, s37, s1
	v_readlane_b32 s6, v243, 9
	v_readlane_b32 s7, v243, 10
	s_add_u32 s0, s0, s6
	s_addc_u32 s1, s1, s7
	s_add_u32 s6, s0, 0x11086000
	s_waitcnt vmcnt(0)
	s_addc_u32 s7, s1, 0
	s_cmp_lg_u32 s3, 0
	s_barrier
	s_cbranch_scc1 .LBB0_1373
	buffer_wbl2 sc1
	s_waitcnt vmcnt(0)
	s_waitcnt vmcnt(0)
	v_or_b32_e32 v0, v150, v145
	v_cmp_eq_u32_e32 vcc, 0, v0
	s_and_saveexec_b64 s[8:9], vcc
	s_cbranch_execz .LBB0_1372
	s_mov_b64 s[10:11], exec
	v_mbcnt_lo_u32_b32 v0, s10, 0
	v_mbcnt_hi_u32_b32 v0, s11, v0
	v_cmp_eq_u32_e32 vcc, 0, v0
	s_and_b64 s[0:1], exec, vcc
	s_mov_b64 exec, s[0:1]
	s_cbranch_execz .LBB0_1372
	s_bcnt1_i32_b64 s0, s[10:11]
	v_mov_b32_e32 v0, s0
	global_atomic_add v185, v0, s[6:7]
